# v41 with MFMA order: k=0 and k=1 MFMAs of the same accumulator back to back
# speedup vs baseline: 1.0236x; 1.0236x over previous
.LBB0_159:
	s_add_u32 s0, s22, 0xfff80080
	s_addc_u32 s1, s23, -1
	s_add_i32 s51, 0, 0x10000
	s_cmp_eq_u32 s50, 28
	s_cselect_b32 s27, s15, s1
	s_cselect_b32 s26, s46, s0
	v_add_u32_e32 v140, s51, v143
	s_cselect_b32 s25, s13, s49
	s_cselect_b32 s24, s47, s48
	s_add_i32 s0, 0, 0x14000
	ds_read_b128 v[146:149], v140
	ds_read_b128 v[150:153], v140 offset:1024
	ds_read_b128 v[154:157], v140 offset:2048
	ds_read_b128 v[158:161], v140 offset:3072
	v_add_u32_e32 v140, s0, v143
	ds_read_b128 v[162:165], v140
	ds_read_b128 v[166:169], v140 offset:1024
	ds_read_b128 v[170:173], v140 offset:2048
	ds_read_b128 v[174:177], v140 offset:3072
	v_lshl_add_u64 v[140:141], s[22:23], 0, v[136:137]
	s_add_i32 m0, s35, 0xc000
	ds_read_b128 v[178:181], v144
	ds_read_b128 v[182:185], v144 offset:1024
	ds_read_b128 v[192:195], v144 offset:2048
	ds_read_b128 v[196:199], v144 offset:3072
	ds_read_b128 v[200:203], v144 offset:4096
	ds_read_b128 v[204:207], v144 offset:5120
	ds_read_b128 v[208:211], v144 offset:6144
	ds_read_b128 v[212:215], v144 offset:7168
	global_load_lds_dwordx4 v[140:141], off
	v_lshl_add_u64 v[140:141], s[22:23], 0, v[138:139]
	s_add_i32 m0, s35, 0xe000
	s_nop 0
	global_load_lds_dwordx4 v[140:141], off
	s_waitcnt vmcnt(8)
	s_waitcnt lgkmcnt(0)
	s_setprio 1
	s_barrier

	v_mfma_f32_16x16x32_bf16 v[126:129], v[146:149], v[178:181], v[126:129]
	v_mfma_f32_16x16x32_bf16 v[126:129], v[150:153], v[182:185], v[126:129]
	v_mfma_f32_16x16x32_bf16 v[118:121], v[154:157], v[178:181], v[118:121]
	v_mfma_f32_16x16x32_bf16 v[118:121], v[158:161], v[182:185], v[118:121]
	v_mfma_f32_16x16x32_bf16 v[110:113], v[146:149], v[192:195], v[110:113]
	v_mfma_f32_16x16x32_bf16 v[110:113], v[150:153], v[196:199], v[110:113]
	v_mfma_f32_16x16x32_bf16 v[102:105], v[154:157], v[192:195], v[102:105]
	v_mfma_f32_16x16x32_bf16 v[102:105], v[158:161], v[196:199], v[102:105]
	v_mfma_f32_16x16x32_bf16 v[94:97], v[146:149], v[200:203], v[94:97]
	v_mfma_f32_16x16x32_bf16 v[94:97], v[150:153], v[204:207], v[94:97]
	v_mfma_f32_16x16x32_bf16 v[86:89], v[154:157], v[200:203], v[86:89]
	v_mfma_f32_16x16x32_bf16 v[86:89], v[158:161], v[204:207], v[86:89]
	v_mfma_f32_16x16x32_bf16 v[78:81], v[146:149], v[208:211], v[78:81]
	v_mfma_f32_16x16x32_bf16 v[78:81], v[150:153], v[212:215], v[78:81]
	v_mfma_f32_16x16x32_bf16 v[70:73], v[154:157], v[208:211], v[70:73]
	v_mfma_f32_16x16x32_bf16 v[70:73], v[158:161], v[212:215], v[70:73]


	v_mfma_f32_16x16x32_bf16 v[122:125], v[162:165], v[178:181], v[122:125]
	v_mfma_f32_16x16x32_bf16 v[122:125], v[166:169], v[182:185], v[122:125]
	v_mfma_f32_16x16x32_bf16 v[114:117], v[170:173], v[178:181], v[114:117]
	v_mfma_f32_16x16x32_bf16 v[114:117], v[174:177], v[182:185], v[114:117]
	v_mfma_f32_16x16x32_bf16 v[106:109], v[162:165], v[192:195], v[106:109]
	v_mfma_f32_16x16x32_bf16 v[106:109], v[166:169], v[196:199], v[106:109]
	v_mfma_f32_16x16x32_bf16 v[98:101], v[170:173], v[192:195], v[98:101]
	v_mfma_f32_16x16x32_bf16 v[98:101], v[174:177], v[196:199], v[98:101]
	v_mfma_f32_16x16x32_bf16 v[90:93], v[162:165], v[200:203], v[90:93]
	v_mfma_f32_16x16x32_bf16 v[90:93], v[166:169], v[204:207], v[90:93]
	v_mfma_f32_16x16x32_bf16 v[82:85], v[170:173], v[200:203], v[82:85]
	v_mfma_f32_16x16x32_bf16 v[82:85], v[174:177], v[204:207], v[82:85]
	v_mfma_f32_16x16x32_bf16 v[74:77], v[162:165], v[208:211], v[74:77]
	v_mfma_f32_16x16x32_bf16 v[74:77], v[166:169], v[212:215], v[74:77]
	v_mfma_f32_16x16x32_bf16 v[66:69], v[170:173], v[208:211], v[66:69]
	v_mfma_f32_16x16x32_bf16 v[66:69], v[174:177], v[212:215], v[66:69]
	s_barrier
	s_setprio 0
	s_add_i32 s1, s51, s31
	v_lshl_add_u64 v[140:141], s[24:25], 0, v[186:187]
	s_mov_b32 m0, s1
	ds_read_b128 v[178:181], v144 offset:16384
	ds_read_b128 v[182:185], v144 offset:17408
	ds_read_b128 v[192:195], v144 offset:18432
	ds_read_b128 v[196:199], v144 offset:19456
	ds_read_b128 v[200:203], v144 offset:20480
	ds_read_b128 v[204:207], v144 offset:21504
	ds_read_b128 v[208:211], v144 offset:22528
	ds_read_b128 v[212:215], v144 offset:23552
	global_load_lds_dwordx4 v[140:141], off
	s_add_i32 m0, s1, 0x2000
	s_add_u32 s52, s24, 0x80000
	v_lshl_add_u64 v[216:217], s[24:25], 0, v[130:131]
	s_addc_u32 s53, s25, 0
	s_add_i32 s0, s0, s31
	global_load_lds_dwordx4 v[216:217], off
	v_lshl_add_u64 v[218:219], s[52:53], 0, v[186:187]
	s_mov_b32 m0, s0
	v_lshl_add_u64 v[220:221], s[26:27], 0, v[132:133]
	global_load_lds_dwordx4 v[218:219], off
	v_lshl_add_u64 v[218:219], s[52:53], 0, v[130:131]
	s_add_i32 m0, s0, 0x2000
	s_nop 0
	global_load_lds_dwordx4 v[218:219], off
	v_lshl_add_u64 v[218:219], s[26:27], 0, v[134:135]
	s_mov_b32 m0, s35
	s_nop 0
	global_load_lds_dwordx4 v[218:219], off
	s_mov_b32 m0, s36
	s_nop 0
	global_load_lds_dwordx4 v[220:221], off
	s_waitcnt vmcnt(8)
	s_waitcnt lgkmcnt(0)
	s_setprio 1
	s_barrier

	v_mfma_f32_16x16x32_bf16 v[62:65], v[146:149], v[178:181], v[62:65]
	v_mfma_f32_16x16x32_bf16 v[62:65], v[150:153], v[182:185], v[62:65]
	v_mfma_f32_16x16x32_bf16 v[54:57], v[154:157], v[178:181], v[54:57]
	v_mfma_f32_16x16x32_bf16 v[54:57], v[158:161], v[182:185], v[54:57]
	v_mfma_f32_16x16x32_bf16 v[46:49], v[146:149], v[192:195], v[46:49]
	v_mfma_f32_16x16x32_bf16 v[46:49], v[150:153], v[196:199], v[46:49]
	v_mfma_f32_16x16x32_bf16 v[38:41], v[154:157], v[192:195], v[38:41]
	v_mfma_f32_16x16x32_bf16 v[38:41], v[158:161], v[196:199], v[38:41]
	v_mfma_f32_16x16x32_bf16 v[30:33], v[146:149], v[200:203], v[30:33]
	v_mfma_f32_16x16x32_bf16 v[30:33], v[150:153], v[204:207], v[30:33]
	v_mfma_f32_16x16x32_bf16 v[22:25], v[154:157], v[200:203], v[22:25]
	v_mfma_f32_16x16x32_bf16 v[22:25], v[158:161], v[204:207], v[22:25]
	v_mfma_f32_16x16x32_bf16 v[14:17], v[146:149], v[208:211], v[14:17]
	v_mfma_f32_16x16x32_bf16 v[14:17], v[150:153], v[212:215], v[14:17]
	v_mfma_f32_16x16x32_bf16 v[6:9], v[154:157], v[208:211], v[6:9]
	v_mfma_f32_16x16x32_bf16 v[6:9], v[158:161], v[212:215], v[6:9]


	v_mfma_f32_16x16x32_bf16 v[58:61], v[162:165], v[178:181], v[58:61]
	v_mfma_f32_16x16x32_bf16 v[58:61], v[166:169], v[182:185], v[58:61]
	v_mfma_f32_16x16x32_bf16 v[50:53], v[170:173], v[178:181], v[50:53]
	v_mfma_f32_16x16x32_bf16 v[50:53], v[174:177], v[182:185], v[50:53]
	v_mfma_f32_16x16x32_bf16 v[42:45], v[162:165], v[192:195], v[42:45]
	v_mfma_f32_16x16x32_bf16 v[42:45], v[166:169], v[196:199], v[42:45]
	v_mfma_f32_16x16x32_bf16 v[34:37], v[170:173], v[192:195], v[34:37]
	v_mfma_f32_16x16x32_bf16 v[34:37], v[174:177], v[196:199], v[34:37]
	v_mfma_f32_16x16x32_bf16 v[26:29], v[162:165], v[200:203], v[26:29]
	v_mfma_f32_16x16x32_bf16 v[26:29], v[166:169], v[204:207], v[26:29]
	v_mfma_f32_16x16x32_bf16 v[18:21], v[170:173], v[200:203], v[18:21]
	v_mfma_f32_16x16x32_bf16 v[18:21], v[174:177], v[204:207], v[18:21]
	v_mfma_f32_16x16x32_bf16 v[10:13], v[162:165], v[208:211], v[10:13]
	v_mfma_f32_16x16x32_bf16 v[10:13], v[166:169], v[212:215], v[10:13]
	v_mfma_f32_16x16x32_bf16 v[2:5], v[170:173], v[208:211], v[2:5]
	v_mfma_f32_16x16x32_bf16 v[2:5], v[174:177], v[212:215], v[2:5]
	s_barrier
	s_setprio 0
	s_add_i32 s0, 0, 0x18000
	v_add_u32_e32 v145, s0, v143
	s_add_i32 s1, 0, 0x1c000
	ds_read_b128 v[146:149], v145
	ds_read_b128 v[150:153], v145 offset:1024
	ds_read_b128 v[154:157], v145 offset:2048
	ds_read_b128 v[158:161], v145 offset:3072
	v_add_u32_e32 v145, s1, v143
	ds_read_b128 v[162:165], v145
	ds_read_b128 v[166:169], v145 offset:1024
	ds_read_b128 v[170:173], v145 offset:2048
	ds_read_b128 v[174:177], v145 offset:3072
	s_add_u32 s26, s26, 0x80000
	s_addc_u32 s27, s27, 0
	s_mov_b32 m0, s37
	v_lshl_add_u64 v[222:223], s[26:27], 0, v[134:135]
	ds_read_b128 v[178:181], v144 offset:32768
	ds_read_b128 v[182:185], v144 offset:33792
	ds_read_b128 v[192:195], v144 offset:34816
	ds_read_b128 v[196:199], v144 offset:35840
	ds_read_b128 v[200:203], v144 offset:36864
	ds_read_b128 v[204:207], v144 offset:37888
	ds_read_b128 v[208:211], v144 offset:38912
	ds_read_b128 v[212:215], v144 offset:39936
	global_load_lds_dwordx4 v[222:223], off
	v_lshl_add_u64 v[222:223], s[26:27], 0, v[132:133]
	s_mov_b32 m0, s38
	s_nop 0
	global_load_lds_dwordx4 v[222:223], off
	s_waitcnt vmcnt(8)
	s_waitcnt lgkmcnt(0)
	s_setprio 1
	s_barrier

	v_mfma_f32_16x16x32_bf16 v[126:129], v[146:149], v[178:181], v[126:129]
	v_mfma_f32_16x16x32_bf16 v[126:129], v[150:153], v[182:185], v[126:129]
	v_mfma_f32_16x16x32_bf16 v[118:121], v[154:157], v[178:181], v[118:121]
	v_mfma_f32_16x16x32_bf16 v[118:121], v[158:161], v[182:185], v[118:121]
	v_mfma_f32_16x16x32_bf16 v[110:113], v[146:149], v[192:195], v[110:113]
	v_mfma_f32_16x16x32_bf16 v[110:113], v[150:153], v[196:199], v[110:113]
	v_mfma_f32_16x16x32_bf16 v[102:105], v[154:157], v[192:195], v[102:105]
	v_mfma_f32_16x16x32_bf16 v[102:105], v[158:161], v[196:199], v[102:105]
	v_mfma_f32_16x16x32_bf16 v[94:97], v[146:149], v[200:203], v[94:97]
	v_mfma_f32_16x16x32_bf16 v[94:97], v[150:153], v[204:207], v[94:97]
	v_mfma_f32_16x16x32_bf16 v[86:89], v[154:157], v[200:203], v[86:89]
	v_mfma_f32_16x16x32_bf16 v[86:89], v[158:161], v[204:207], v[86:89]
	v_mfma_f32_16x16x32_bf16 v[78:81], v[146:149], v[208:211], v[78:81]
	v_mfma_f32_16x16x32_bf16 v[78:81], v[150:153], v[212:215], v[78:81]
	v_mfma_f32_16x16x32_bf16 v[70:73], v[154:157], v[208:211], v[70:73]
	v_mfma_f32_16x16x32_bf16 v[70:73], v[158:161], v[212:215], v[70:73]


	v_mfma_f32_16x16x32_bf16 v[122:125], v[162:165], v[178:181], v[122:125]
	v_mfma_f32_16x16x32_bf16 v[122:125], v[166:169], v[182:185], v[122:125]
	v_mfma_f32_16x16x32_bf16 v[114:117], v[170:173], v[178:181], v[114:117]
	v_mfma_f32_16x16x32_bf16 v[114:117], v[174:177], v[182:185], v[114:117]
	v_mfma_f32_16x16x32_bf16 v[106:109], v[162:165], v[192:195], v[106:109]
	v_mfma_f32_16x16x32_bf16 v[106:109], v[166:169], v[196:199], v[106:109]
	v_mfma_f32_16x16x32_bf16 v[98:101], v[170:173], v[192:195], v[98:101]
	v_mfma_f32_16x16x32_bf16 v[98:101], v[174:177], v[196:199], v[98:101]
	v_mfma_f32_16x16x32_bf16 v[90:93], v[162:165], v[200:203], v[90:93]
	v_mfma_f32_16x16x32_bf16 v[90:93], v[166:169], v[204:207], v[90:93]
	v_mfma_f32_16x16x32_bf16 v[82:85], v[170:173], v[200:203], v[82:85]
	v_mfma_f32_16x16x32_bf16 v[82:85], v[174:177], v[204:207], v[82:85]
	v_mfma_f32_16x16x32_bf16 v[74:77], v[162:165], v[208:211], v[74:77]
	v_mfma_f32_16x16x32_bf16 v[74:77], v[166:169], v[212:215], v[74:77]
	v_mfma_f32_16x16x32_bf16 v[66:69], v[170:173], v[208:211], v[66:69]
	v_mfma_f32_16x16x32_bf16 v[66:69], v[174:177], v[212:215], v[66:69]
	s_barrier
	s_setprio 0
	s_add_i32 s0, s0, s31
	v_lshl_add_u64 v[140:141], v[140:141], 0, s[84:85]
	s_mov_b32 m0, s0
	ds_read_b128 v[178:181], v144 offset:49152
	ds_read_b128 v[182:185], v144 offset:50176
	ds_read_b128 v[192:195], v144 offset:51200
	ds_read_b128 v[196:199], v144 offset:52224
	ds_read_b128 v[200:203], v144 offset:53248
	ds_read_b128 v[204:207], v144 offset:54272
	ds_read_b128 v[208:211], v144 offset:55296
	ds_read_b128 v[212:215], v144 offset:56320
	global_load_lds_dwordx4 v[140:141], off
	s_add_i32 m0, s0, 0x2000
	s_add_u32 s24, s24, 0x80080
	v_lshl_add_u64 v[140:141], v[216:217], 0, s[84:85]
	s_addc_u32 s25, s25, 0
	s_add_i32 s0, s1, s31
	global_load_lds_dwordx4 v[140:141], off
	v_lshl_add_u64 v[140:141], s[24:25], 0, v[186:187]
	s_mov_b32 m0, s0
	s_nop 0
	global_load_lds_dwordx4 v[140:141], off
	v_lshl_add_u64 v[140:141], s[24:25], 0, v[130:131]
	s_add_i32 m0, s0, 0x2000
	s_nop 0
	global_load_lds_dwordx4 v[140:141], off
	v_lshl_add_u64 v[140:141], v[218:219], 0, s[84:85]
	s_mov_b32 m0, s39
	s_nop 0
	global_load_lds_dwordx4 v[140:141], off
	v_lshl_add_u64 v[140:141], v[220:221], 0, s[84:85]
	s_mov_b32 m0, s40
	s_nop 0
	global_load_lds_dwordx4 v[140:141], off
	s_waitcnt vmcnt(8)
	s_waitcnt lgkmcnt(0)
	s_setprio 1
	s_barrier

	v_mfma_f32_16x16x32_bf16 v[62:65], v[146:149], v[178:181], v[62:65]
	v_mfma_f32_16x16x32_bf16 v[62:65], v[150:153], v[182:185], v[62:65]
	v_mfma_f32_16x16x32_bf16 v[54:57], v[154:157], v[178:181], v[54:57]
	v_mfma_f32_16x16x32_bf16 v[54:57], v[158:161], v[182:185], v[54:57]
	v_mfma_f32_16x16x32_bf16 v[46:49], v[146:149], v[192:195], v[46:49]
	v_mfma_f32_16x16x32_bf16 v[46:49], v[150:153], v[196:199], v[46:49]
	v_mfma_f32_16x16x32_bf16 v[38:41], v[154:157], v[192:195], v[38:41]
	v_mfma_f32_16x16x32_bf16 v[38:41], v[158:161], v[196:199], v[38:41]
	v_mfma_f32_16x16x32_bf16 v[30:33], v[146:149], v[200:203], v[30:33]
	v_mfma_f32_16x16x32_bf16 v[30:33], v[150:153], v[204:207], v[30:33]
	v_mfma_f32_16x16x32_bf16 v[22:25], v[154:157], v[200:203], v[22:25]
	v_mfma_f32_16x16x32_bf16 v[22:25], v[158:161], v[204:207], v[22:25]
	v_mfma_f32_16x16x32_bf16 v[14:17], v[146:149], v[208:211], v[14:17]
	v_mfma_f32_16x16x32_bf16 v[14:17], v[150:153], v[212:215], v[14:17]
	v_mfma_f32_16x16x32_bf16 v[6:9], v[154:157], v[208:211], v[6:9]
	v_mfma_f32_16x16x32_bf16 v[6:9], v[158:161], v[212:215], v[6:9]


	v_mfma_f32_16x16x32_bf16 v[58:61], v[162:165], v[178:181], v[58:61]
	v_mfma_f32_16x16x32_bf16 v[58:61], v[166:169], v[182:185], v[58:61]
	v_mfma_f32_16x16x32_bf16 v[50:53], v[170:173], v[178:181], v[50:53]
	v_mfma_f32_16x16x32_bf16 v[50:53], v[174:177], v[182:185], v[50:53]
	v_mfma_f32_16x16x32_bf16 v[42:45], v[162:165], v[192:195], v[42:45]
	v_mfma_f32_16x16x32_bf16 v[42:45], v[166:169], v[196:199], v[42:45]
	v_mfma_f32_16x16x32_bf16 v[34:37], v[170:173], v[192:195], v[34:37]
	v_mfma_f32_16x16x32_bf16 v[34:37], v[174:177], v[196:199], v[34:37]
	v_mfma_f32_16x16x32_bf16 v[26:29], v[162:165], v[200:203], v[26:29]
	v_mfma_f32_16x16x32_bf16 v[26:29], v[166:169], v[204:207], v[26:29]
	v_mfma_f32_16x16x32_bf16 v[18:21], v[170:173], v[200:203], v[18:21]
	v_mfma_f32_16x16x32_bf16 v[18:21], v[174:177], v[204:207], v[18:21]
	v_mfma_f32_16x16x32_bf16 v[10:13], v[162:165], v[208:211], v[10:13]
	v_mfma_f32_16x16x32_bf16 v[10:13], v[166:169], v[212:215], v[10:13]
	v_mfma_f32_16x16x32_bf16 v[2:5], v[170:173], v[208:211], v[2:5]
	v_mfma_f32_16x16x32_bf16 v[2:5], v[174:177], v[212:215], v[2:5]
	s_barrier
	s_setprio 0
	s_add_i32 s50, s50, 2
	s_add_u32 s22, s22, 0x100
	s_addc_u32 s23, s23, 0
	s_add_u32 s48, s48, 0x100
	s_addc_u32 s49, s49, 0
	s_cmp_gt_u32 s50, 29
	s_cbranch_scc0 .LBB0_159
	s_and_b64 vcc, exec, s[10:11]
	s_cbranch_vccz .LBB0_162
	s_barrier

.LBB0_243:
	s_add_u32 s22, s20, 0x100
	s_addc_u32 s23, s21, 0
	s_add_i32 s0, 0, 0x10000
	s_cmpk_eq_i32 s51, 0x54
	s_cselect_b32 s27, s7, s23
	s_cselect_b32 s26, s6, s22
	s_cselect_b32 s25, s19, s50
	s_cselect_b32 s24, s18, s49
	s_add_i32 s1, 0, 0x14000
	v_add_u32_e32 v126, s0, v237
	v_add_u32_e32 v158, s1, v237
	ds_read_b128 v[90:93], v126
	ds_read_b128 v[102:105], v126 offset:1024
	ds_read_b128 v[114:117], v126 offset:2048
	ds_read_b128 v[126:129], v126 offset:3072
	ds_read_b128 v[138:141], v158
	ds_read_b128 v[142:145], v158 offset:1024
	ds_read_b128 v[154:157], v158 offset:2048
	ds_read_b128 v[158:161], v158 offset:3072
	v_lshl_add_u64 v[210:211], s[20:21], 0, v[198:199]
	s_add_i32 m0, s34, 0xc000
	ds_read_b128 v[162:165], v238
	ds_read_b128 v[166:169], v238 offset:1024
	ds_read_b128 v[170:173], v238 offset:2048
	ds_read_b128 v[174:177], v238 offset:3072
	ds_read_b128 v[178:181], v238 offset:4096
	ds_read_b128 v[182:185], v238 offset:5120
	ds_read_b128 v[202:205], v238 offset:6144
	ds_read_b128 v[206:209], v238 offset:7168
	global_load_lds_dwordx4 v[210:211], off
	v_lshl_add_u64 v[210:211], s[20:21], 0, v[200:201]
	s_add_i32 m0, s34, 0xe000
	s_nop 0
	global_load_lds_dwordx4 v[210:211], off
	s_waitcnt vmcnt(8)
	s_waitcnt lgkmcnt(0)
	s_setprio 1
	s_barrier

	v_mfma_f32_16x16x32_bf16 v[150:153], v[90:93], v[162:165], v[150:153]
	v_mfma_f32_16x16x32_bf16 v[150:153], v[102:105], v[166:169], v[150:153]
	v_mfma_f32_16x16x32_bf16 v[146:149], v[114:117], v[162:165], v[146:149]
	v_mfma_f32_16x16x32_bf16 v[146:149], v[126:129], v[166:169], v[146:149]
	v_mfma_f32_16x16x32_bf16 v[122:125], v[90:93], v[170:173], v[122:125]
	v_mfma_f32_16x16x32_bf16 v[122:125], v[102:105], v[174:177], v[122:125]
	v_mfma_f32_16x16x32_bf16 v[118:121], v[114:117], v[170:173], v[118:121]
	v_mfma_f32_16x16x32_bf16 v[118:121], v[126:129], v[174:177], v[118:121]
	v_mfma_f32_16x16x32_bf16 v[98:101], v[90:93], v[178:181], v[98:101]
	v_mfma_f32_16x16x32_bf16 v[98:101], v[102:105], v[182:185], v[98:101]
	v_mfma_f32_16x16x32_bf16 v[94:97], v[114:117], v[178:181], v[94:97]
	v_mfma_f32_16x16x32_bf16 v[94:97], v[126:129], v[182:185], v[94:97]
	v_mfma_f32_16x16x32_bf16 v[78:81], v[90:93], v[202:205], v[78:81]
	v_mfma_f32_16x16x32_bf16 v[78:81], v[102:105], v[206:209], v[78:81]
	v_mfma_f32_16x16x32_bf16 v[74:77], v[114:117], v[202:205], v[74:77]
	v_mfma_f32_16x16x32_bf16 v[74:77], v[126:129], v[206:209], v[74:77]


	v_mfma_f32_16x16x32_bf16 v[134:137], v[138:141], v[162:165], v[134:137]
	v_mfma_f32_16x16x32_bf16 v[134:137], v[142:145], v[166:169], v[134:137]
	v_mfma_f32_16x16x32_bf16 v[130:133], v[154:157], v[162:165], v[130:133]
	v_mfma_f32_16x16x32_bf16 v[130:133], v[158:161], v[166:169], v[130:133]
	v_mfma_f32_16x16x32_bf16 v[110:113], v[138:141], v[170:173], v[110:113]
	v_mfma_f32_16x16x32_bf16 v[110:113], v[142:145], v[174:177], v[110:113]
	v_mfma_f32_16x16x32_bf16 v[106:109], v[154:157], v[170:173], v[106:109]
	v_mfma_f32_16x16x32_bf16 v[106:109], v[158:161], v[174:177], v[106:109]
	v_mfma_f32_16x16x32_bf16 v[86:89], v[138:141], v[178:181], v[86:89]
	v_mfma_f32_16x16x32_bf16 v[86:89], v[142:145], v[182:185], v[86:89]
	v_mfma_f32_16x16x32_bf16 v[82:85], v[154:157], v[178:181], v[82:85]
	v_mfma_f32_16x16x32_bf16 v[82:85], v[158:161], v[182:185], v[82:85]
	v_mfma_f32_16x16x32_bf16 v[70:73], v[138:141], v[202:205], v[70:73]
	v_mfma_f32_16x16x32_bf16 v[70:73], v[142:145], v[206:209], v[70:73]
	v_mfma_f32_16x16x32_bf16 v[66:69], v[154:157], v[202:205], v[66:69]
	v_mfma_f32_16x16x32_bf16 v[66:69], v[158:161], v[206:209], v[66:69]
	s_barrier
	s_setprio 0
	s_add_i32 s0, s0, s31
	v_lshl_add_u64 v[210:211], s[24:25], 0, v[186:187]
	s_mov_b32 m0, s0
	ds_read_b128 v[162:165], v238 offset:16384
	ds_read_b128 v[166:169], v238 offset:17408
	ds_read_b128 v[170:173], v238 offset:18432
	ds_read_b128 v[174:177], v238 offset:19456
	ds_read_b128 v[178:181], v238 offset:20480
	ds_read_b128 v[182:185], v238 offset:21504
	ds_read_b128 v[202:205], v238 offset:22528
	ds_read_b128 v[206:209], v238 offset:23552
	global_load_lds_dwordx4 v[210:211], off
	s_add_i32 m0, s0, 0x2000
	s_add_u32 s20, s24, 0x160000
	v_lshl_add_u64 v[212:213], s[24:25], 0, v[196:197]
	s_addc_u32 s21, s25, 0
	s_add_i32 s0, s1, s31
	global_load_lds_dwordx4 v[212:213], off
	v_lshl_add_u64 v[214:215], s[20:21], 0, v[186:187]
	s_mov_b32 m0, s0
	v_lshl_add_u64 v[216:217], s[26:27], 0, v[194:195]
	global_load_lds_dwordx4 v[214:215], off
	v_lshl_add_u64 v[214:215], s[20:21], 0, v[196:197]
	s_add_i32 m0, s0, 0x2000
	s_nop 0
	global_load_lds_dwordx4 v[214:215], off
	v_lshl_add_u64 v[214:215], s[26:27], 0, v[192:193]
	s_mov_b32 m0, s34
	s_nop 0
	global_load_lds_dwordx4 v[214:215], off
	s_mov_b32 m0, s35
	s_nop 0
	global_load_lds_dwordx4 v[216:217], off
	s_waitcnt vmcnt(8)
	s_waitcnt lgkmcnt(0)
	s_setprio 1
	s_barrier

	v_mfma_f32_16x16x32_bf16 v[62:65], v[90:93], v[162:165], v[62:65]
	v_mfma_f32_16x16x32_bf16 v[62:65], v[102:105], v[166:169], v[62:65]
	v_mfma_f32_16x16x32_bf16 v[58:61], v[114:117], v[162:165], v[58:61]
	v_mfma_f32_16x16x32_bf16 v[58:61], v[126:129], v[166:169], v[58:61]
	v_mfma_f32_16x16x32_bf16 v[46:49], v[90:93], v[170:173], v[46:49]
	v_mfma_f32_16x16x32_bf16 v[46:49], v[102:105], v[174:177], v[46:49]
	v_mfma_f32_16x16x32_bf16 v[42:45], v[114:117], v[170:173], v[42:45]
	v_mfma_f32_16x16x32_bf16 v[42:45], v[126:129], v[174:177], v[42:45]
	v_mfma_f32_16x16x32_bf16 v[30:33], v[90:93], v[178:181], v[30:33]
	v_mfma_f32_16x16x32_bf16 v[30:33], v[102:105], v[182:185], v[30:33]
	v_mfma_f32_16x16x32_bf16 v[26:29], v[114:117], v[178:181], v[26:29]
	v_mfma_f32_16x16x32_bf16 v[26:29], v[126:129], v[182:185], v[26:29]
	v_mfma_f32_16x16x32_bf16 v[14:17], v[90:93], v[202:205], v[14:17]
	v_mfma_f32_16x16x32_bf16 v[14:17], v[102:105], v[206:209], v[14:17]
	v_mfma_f32_16x16x32_bf16 v[10:13], v[114:117], v[202:205], v[10:13]
	v_mfma_f32_16x16x32_bf16 v[10:13], v[126:129], v[206:209], v[10:13]


	v_mfma_f32_16x16x32_bf16 v[54:57], v[138:141], v[162:165], v[54:57]
	v_mfma_f32_16x16x32_bf16 v[54:57], v[142:145], v[166:169], v[54:57]
	v_mfma_f32_16x16x32_bf16 v[50:53], v[154:157], v[162:165], v[50:53]
	v_mfma_f32_16x16x32_bf16 v[50:53], v[158:161], v[166:169], v[50:53]
	v_mfma_f32_16x16x32_bf16 v[38:41], v[138:141], v[170:173], v[38:41]
	v_mfma_f32_16x16x32_bf16 v[38:41], v[142:145], v[174:177], v[38:41]
	v_mfma_f32_16x16x32_bf16 v[34:37], v[154:157], v[170:173], v[34:37]
	v_mfma_f32_16x16x32_bf16 v[34:37], v[158:161], v[174:177], v[34:37]
	v_mfma_f32_16x16x32_bf16 v[22:25], v[138:141], v[178:181], v[22:25]
	v_mfma_f32_16x16x32_bf16 v[22:25], v[142:145], v[182:185], v[22:25]
	v_mfma_f32_16x16x32_bf16 v[18:21], v[154:157], v[178:181], v[18:21]
	v_mfma_f32_16x16x32_bf16 v[18:21], v[158:161], v[182:185], v[18:21]
	v_mfma_f32_16x16x32_bf16 v[6:9], v[138:141], v[202:205], v[6:9]
	v_mfma_f32_16x16x32_bf16 v[6:9], v[142:145], v[206:209], v[6:9]
	v_mfma_f32_16x16x32_bf16 v[2:5], v[154:157], v[202:205], v[2:5]
	v_mfma_f32_16x16x32_bf16 v[2:5], v[158:161], v[206:209], v[2:5]
	s_barrier
	s_setprio 0
	s_add_i32 s0, 0, 0x18000
	s_add_i32 s1, 0, 0x1c000
	v_add_u32_e32 v126, s0, v237
	v_add_u32_e32 v158, s1, v237
	ds_read_b128 v[90:93], v126
	ds_read_b128 v[102:105], v126 offset:1024
	ds_read_b128 v[114:117], v126 offset:2048
	ds_read_b128 v[126:129], v126 offset:3072
	ds_read_b128 v[138:141], v158
	ds_read_b128 v[142:145], v158 offset:1024
	ds_read_b128 v[154:157], v158 offset:2048
	ds_read_b128 v[158:161], v158 offset:3072
	s_add_u32 s20, s26, 0x160000
	s_addc_u32 s21, s27, 0
	s_mov_b32 m0, s36
	v_lshl_add_u64 v[218:219], s[20:21], 0, v[192:193]
	ds_read_b128 v[162:165], v238 offset:32768
	ds_read_b128 v[166:169], v238 offset:33792
	ds_read_b128 v[170:173], v238 offset:34816
	ds_read_b128 v[174:177], v238 offset:35840
	ds_read_b128 v[178:181], v238 offset:36864
	ds_read_b128 v[182:185], v238 offset:37888
	ds_read_b128 v[202:205], v238 offset:38912
	ds_read_b128 v[206:209], v238 offset:39936
	global_load_lds_dwordx4 v[218:219], off
	v_lshl_add_u64 v[218:219], s[20:21], 0, v[194:195]
	s_mov_b32 m0, s37
	s_nop 0
	global_load_lds_dwordx4 v[218:219], off
	s_waitcnt vmcnt(8)
	s_waitcnt lgkmcnt(0)
	s_setprio 1
	s_barrier

	v_mfma_f32_16x16x32_bf16 v[150:153], v[90:93], v[162:165], v[150:153]
	v_mfma_f32_16x16x32_bf16 v[150:153], v[102:105], v[166:169], v[150:153]
	v_mfma_f32_16x16x32_bf16 v[146:149], v[114:117], v[162:165], v[146:149]
	v_mfma_f32_16x16x32_bf16 v[146:149], v[126:129], v[166:169], v[146:149]
	v_mfma_f32_16x16x32_bf16 v[122:125], v[90:93], v[170:173], v[122:125]
	v_mfma_f32_16x16x32_bf16 v[122:125], v[102:105], v[174:177], v[122:125]
	v_mfma_f32_16x16x32_bf16 v[118:121], v[114:117], v[170:173], v[118:121]
	v_mfma_f32_16x16x32_bf16 v[118:121], v[126:129], v[174:177], v[118:121]
	v_mfma_f32_16x16x32_bf16 v[98:101], v[90:93], v[178:181], v[98:101]
	v_mfma_f32_16x16x32_bf16 v[98:101], v[102:105], v[182:185], v[98:101]
	v_mfma_f32_16x16x32_bf16 v[94:97], v[114:117], v[178:181], v[94:97]
	v_mfma_f32_16x16x32_bf16 v[94:97], v[126:129], v[182:185], v[94:97]
	v_mfma_f32_16x16x32_bf16 v[78:81], v[90:93], v[202:205], v[78:81]
	v_mfma_f32_16x16x32_bf16 v[78:81], v[102:105], v[206:209], v[78:81]
	v_mfma_f32_16x16x32_bf16 v[74:77], v[114:117], v[202:205], v[74:77]
	v_mfma_f32_16x16x32_bf16 v[74:77], v[126:129], v[206:209], v[74:77]


	v_mfma_f32_16x16x32_bf16 v[134:137], v[138:141], v[162:165], v[134:137]
	v_mfma_f32_16x16x32_bf16 v[134:137], v[142:145], v[166:169], v[134:137]
	v_mfma_f32_16x16x32_bf16 v[130:133], v[154:157], v[162:165], v[130:133]
	v_mfma_f32_16x16x32_bf16 v[130:133], v[158:161], v[166:169], v[130:133]
	v_mfma_f32_16x16x32_bf16 v[110:113], v[138:141], v[170:173], v[110:113]
	v_mfma_f32_16x16x32_bf16 v[110:113], v[142:145], v[174:177], v[110:113]
	v_mfma_f32_16x16x32_bf16 v[106:109], v[154:157], v[170:173], v[106:109]
	v_mfma_f32_16x16x32_bf16 v[106:109], v[158:161], v[174:177], v[106:109]
	v_mfma_f32_16x16x32_bf16 v[86:89], v[138:141], v[178:181], v[86:89]
	v_mfma_f32_16x16x32_bf16 v[86:89], v[142:145], v[182:185], v[86:89]
	v_mfma_f32_16x16x32_bf16 v[82:85], v[154:157], v[178:181], v[82:85]
	v_mfma_f32_16x16x32_bf16 v[82:85], v[158:161], v[182:185], v[82:85]
	v_mfma_f32_16x16x32_bf16 v[70:73], v[138:141], v[202:205], v[70:73]
	v_mfma_f32_16x16x32_bf16 v[70:73], v[142:145], v[206:209], v[70:73]
	v_mfma_f32_16x16x32_bf16 v[66:69], v[154:157], v[202:205], v[66:69]
	v_mfma_f32_16x16x32_bf16 v[66:69], v[158:161], v[206:209], v[66:69]
	s_barrier
	s_setprio 0
	s_add_i32 s0, s0, s31
	v_lshl_add_u64 v[210:211], v[210:211], 0, s[84:85]
	s_mov_b32 m0, s0
	ds_read_b128 v[162:165], v238 offset:49152
	ds_read_b128 v[166:169], v238 offset:50176
	ds_read_b128 v[170:173], v238 offset:51200
	ds_read_b128 v[174:177], v238 offset:52224
	ds_read_b128 v[178:181], v238 offset:53248
	ds_read_b128 v[182:185], v238 offset:54272
	ds_read_b128 v[202:205], v238 offset:55296
	ds_read_b128 v[206:209], v238 offset:56320
	global_load_lds_dwordx4 v[210:211], off
	s_add_i32 m0, s0, 0x2000
	s_add_u32 s20, s24, 0x160080
	v_lshl_add_u64 v[210:211], v[212:213], 0, s[84:85]
	s_addc_u32 s21, s25, 0
	s_add_i32 s0, s1, s31
	global_load_lds_dwordx4 v[210:211], off
	v_lshl_add_u64 v[210:211], s[20:21], 0, v[186:187]
	s_mov_b32 m0, s0
	s_nop 0
	global_load_lds_dwordx4 v[210:211], off
	v_lshl_add_u64 v[210:211], s[20:21], 0, v[196:197]
	s_add_i32 m0, s0, 0x2000
	s_nop 0
	global_load_lds_dwordx4 v[210:211], off
	v_lshl_add_u64 v[210:211], v[214:215], 0, s[84:85]
	s_mov_b32 m0, s41
	s_nop 0
	global_load_lds_dwordx4 v[210:211], off
	v_lshl_add_u64 v[210:211], v[216:217], 0, s[84:85]
	s_mov_b32 m0, s42
	s_nop 0
	global_load_lds_dwordx4 v[210:211], off
	s_waitcnt vmcnt(8)
	s_waitcnt lgkmcnt(0)
	s_setprio 1
	s_barrier

	v_mfma_f32_16x16x32_bf16 v[62:65], v[90:93], v[162:165], v[62:65]
	v_mfma_f32_16x16x32_bf16 v[62:65], v[102:105], v[166:169], v[62:65]
	v_mfma_f32_16x16x32_bf16 v[58:61], v[114:117], v[162:165], v[58:61]
	v_mfma_f32_16x16x32_bf16 v[58:61], v[126:129], v[166:169], v[58:61]
	v_mfma_f32_16x16x32_bf16 v[46:49], v[90:93], v[170:173], v[46:49]
	v_mfma_f32_16x16x32_bf16 v[46:49], v[102:105], v[174:177], v[46:49]
	v_mfma_f32_16x16x32_bf16 v[42:45], v[114:117], v[170:173], v[42:45]
	v_mfma_f32_16x16x32_bf16 v[42:45], v[126:129], v[174:177], v[42:45]
	v_mfma_f32_16x16x32_bf16 v[30:33], v[90:93], v[178:181], v[30:33]
	v_mfma_f32_16x16x32_bf16 v[30:33], v[102:105], v[182:185], v[30:33]
	v_mfma_f32_16x16x32_bf16 v[26:29], v[114:117], v[178:181], v[26:29]
	v_mfma_f32_16x16x32_bf16 v[26:29], v[126:129], v[182:185], v[26:29]
	v_mfma_f32_16x16x32_bf16 v[14:17], v[90:93], v[202:205], v[14:17]
	v_mfma_f32_16x16x32_bf16 v[14:17], v[102:105], v[206:209], v[14:17]
	v_mfma_f32_16x16x32_bf16 v[10:13], v[114:117], v[202:205], v[10:13]
	v_mfma_f32_16x16x32_bf16 v[10:13], v[126:129], v[206:209], v[10:13]


	v_mfma_f32_16x16x32_bf16 v[54:57], v[138:141], v[162:165], v[54:57]
	v_mfma_f32_16x16x32_bf16 v[54:57], v[142:145], v[166:169], v[54:57]
	v_mfma_f32_16x16x32_bf16 v[50:53], v[154:157], v[162:165], v[50:53]
	v_mfma_f32_16x16x32_bf16 v[50:53], v[158:161], v[166:169], v[50:53]
	v_mfma_f32_16x16x32_bf16 v[38:41], v[138:141], v[170:173], v[38:41]
	v_mfma_f32_16x16x32_bf16 v[38:41], v[142:145], v[174:177], v[38:41]
	v_mfma_f32_16x16x32_bf16 v[34:37], v[154:157], v[170:173], v[34:37]
	v_mfma_f32_16x16x32_bf16 v[34:37], v[158:161], v[174:177], v[34:37]
	v_mfma_f32_16x16x32_bf16 v[22:25], v[138:141], v[178:181], v[22:25]
	v_mfma_f32_16x16x32_bf16 v[22:25], v[142:145], v[182:185], v[22:25]
	v_mfma_f32_16x16x32_bf16 v[18:21], v[154:157], v[178:181], v[18:21]
	v_mfma_f32_16x16x32_bf16 v[18:21], v[158:161], v[182:185], v[18:21]
	v_mfma_f32_16x16x32_bf16 v[6:9], v[138:141], v[202:205], v[6:9]
	v_mfma_f32_16x16x32_bf16 v[6:9], v[142:145], v[206:209], v[6:9]
	v_mfma_f32_16x16x32_bf16 v[2:5], v[154:157], v[202:205], v[2:5]
	v_mfma_f32_16x16x32_bf16 v[2:5], v[158:161], v[206:209], v[2:5]
	s_barrier
	s_setprio 0
	s_add_i32 s51, s51, 2
	s_add_u32 s49, s49, 0x100
	s_addc_u32 s50, s50, 0
	s_cmpk_gt_u32 s51, 0x55
	s_mov_b64 s[20:21], s[22:23]
	s_cbranch_scc0 .LBB0_243
	s_and_b64 vcc, exec, s[16:17]
	s_cbranch_vccz .LBB0_246
	s_barrier

.LBB0_443:
	s_add_u32 s0, s26, 0xfff80080
	s_addc_u32 s1, s27, -1
	s_add_i32 s56, 0, 0x10000
	s_cmp_eq_u32 s55, 28
	s_cselect_b32 s31, s19, s1
	s_cselect_b32 s30, s51, s0
	v_add_u32_e32 v140, s56, v144
	s_cselect_b32 s29, s17, s54
	s_cselect_b32 s28, s52, s53
	s_add_i32 s0, 0, 0x14000
	ds_read_b128 v[146:149], v140
	ds_read_b128 v[150:153], v140 offset:1024
	ds_read_b128 v[154:157], v140 offset:2048
	ds_read_b128 v[158:161], v140 offset:3072
	v_add_u32_e32 v140, s0, v144
	ds_read_b128 v[162:165], v140
	ds_read_b128 v[166:169], v140 offset:1024
	ds_read_b128 v[170:173], v140 offset:2048
	ds_read_b128 v[174:177], v140 offset:3072
	v_lshl_add_u64 v[140:141], s[26:27], 0, v[136:137]
	s_add_i32 m0, s25, 0xc000
	ds_read_b128 v[178:181], v145
	ds_read_b128 v[182:185], v145 offset:1024
	ds_read_b128 v[192:195], v145 offset:2048
	ds_read_b128 v[196:199], v145 offset:3072
	ds_read_b128 v[200:203], v145 offset:4096
	ds_read_b128 v[204:207], v145 offset:5120
	ds_read_b128 v[208:211], v145 offset:6144
	ds_read_b128 v[212:215], v145 offset:7168
	global_load_lds_dwordx4 v[140:141], off
	v_lshl_add_u64 v[140:141], s[26:27], 0, v[138:139]
	s_add_i32 m0, s25, 0xe000
	s_nop 0
	global_load_lds_dwordx4 v[140:141], off
	s_waitcnt vmcnt(8)
	s_waitcnt lgkmcnt(0)
	s_setprio 1
	s_barrier

	v_mfma_f32_16x16x32_bf16 v[126:129], v[146:149], v[178:181], v[126:129]
	v_mfma_f32_16x16x32_bf16 v[126:129], v[150:153], v[182:185], v[126:129]
	v_mfma_f32_16x16x32_bf16 v[122:125], v[154:157], v[178:181], v[122:125]
	v_mfma_f32_16x16x32_bf16 v[122:125], v[158:161], v[182:185], v[122:125]
	v_mfma_f32_16x16x32_bf16 v[114:117], v[146:149], v[192:195], v[114:117]
	v_mfma_f32_16x16x32_bf16 v[114:117], v[150:153], v[196:199], v[114:117]
	v_mfma_f32_16x16x32_bf16 v[106:109], v[154:157], v[192:195], v[106:109]
	v_mfma_f32_16x16x32_bf16 v[106:109], v[158:161], v[196:199], v[106:109]
	v_mfma_f32_16x16x32_bf16 v[98:101], v[146:149], v[200:203], v[98:101]
	v_mfma_f32_16x16x32_bf16 v[98:101], v[150:153], v[204:207], v[98:101]
	v_mfma_f32_16x16x32_bf16 v[90:93], v[154:157], v[200:203], v[90:93]
	v_mfma_f32_16x16x32_bf16 v[90:93], v[158:161], v[204:207], v[90:93]
	v_mfma_f32_16x16x32_bf16 v[82:85], v[146:149], v[208:211], v[82:85]
	v_mfma_f32_16x16x32_bf16 v[82:85], v[150:153], v[212:215], v[82:85]
	v_mfma_f32_16x16x32_bf16 v[74:77], v[154:157], v[208:211], v[74:77]
	v_mfma_f32_16x16x32_bf16 v[74:77], v[158:161], v[212:215], v[74:77]


	v_mfma_f32_16x16x32_bf16 v[118:121], v[162:165], v[178:181], v[118:121]
	v_mfma_f32_16x16x32_bf16 v[118:121], v[166:169], v[182:185], v[118:121]
	v_mfma_f32_16x16x32_bf16 v[110:113], v[170:173], v[178:181], v[110:113]
	v_mfma_f32_16x16x32_bf16 v[110:113], v[174:177], v[182:185], v[110:113]
	v_mfma_f32_16x16x32_bf16 v[102:105], v[162:165], v[192:195], v[102:105]
	v_mfma_f32_16x16x32_bf16 v[102:105], v[166:169], v[196:199], v[102:105]
	v_mfma_f32_16x16x32_bf16 v[94:97], v[170:173], v[192:195], v[94:97]
	v_mfma_f32_16x16x32_bf16 v[94:97], v[174:177], v[196:199], v[94:97]
	v_mfma_f32_16x16x32_bf16 v[86:89], v[162:165], v[200:203], v[86:89]
	v_mfma_f32_16x16x32_bf16 v[86:89], v[166:169], v[204:207], v[86:89]
	v_mfma_f32_16x16x32_bf16 v[78:81], v[170:173], v[200:203], v[78:81]
	v_mfma_f32_16x16x32_bf16 v[78:81], v[174:177], v[204:207], v[78:81]
	v_mfma_f32_16x16x32_bf16 v[70:73], v[162:165], v[208:211], v[70:73]
	v_mfma_f32_16x16x32_bf16 v[70:73], v[166:169], v[212:215], v[70:73]
	v_mfma_f32_16x16x32_bf16 v[66:69], v[170:173], v[208:211], v[66:69]
	v_mfma_f32_16x16x32_bf16 v[66:69], v[174:177], v[212:215], v[66:69]
	s_barrier
	s_setprio 0
	s_add_i32 s1, s56, s39
	v_lshl_add_u64 v[140:141], s[28:29], 0, v[186:187]
	s_mov_b32 m0, s1
	ds_read_b128 v[178:181], v145 offset:16384
	ds_read_b128 v[182:185], v145 offset:17408
	ds_read_b128 v[192:195], v145 offset:18432
	ds_read_b128 v[196:199], v145 offset:19456
	ds_read_b128 v[200:203], v145 offset:20480
	ds_read_b128 v[204:207], v145 offset:21504
	ds_read_b128 v[208:211], v145 offset:22528
	ds_read_b128 v[212:215], v145 offset:23552
	global_load_lds_dwordx4 v[140:141], off
	s_add_i32 m0, s1, 0x2000
	s_add_u32 s56, s28, 0x80000
	v_lshl_add_u64 v[188:189], s[28:29], 0, v[130:131]
	s_addc_u32 s57, s29, 0
	s_add_i32 s0, s0, s39
	global_load_lds_dwordx4 v[188:189], off
	v_lshl_add_u64 v[216:217], s[56:57], 0, v[186:187]
	s_mov_b32 m0, s0
	v_lshl_add_u64 v[218:219], s[30:31], 0, v[132:133]
	global_load_lds_dwordx4 v[216:217], off
	v_lshl_add_u64 v[216:217], s[56:57], 0, v[130:131]
	s_add_i32 m0, s0, 0x2000
	s_nop 0
	global_load_lds_dwordx4 v[216:217], off
	v_lshl_add_u64 v[216:217], s[30:31], 0, v[134:135]
	s_mov_b32 m0, s25
	s_nop 0
	global_load_lds_dwordx4 v[216:217], off
	s_mov_b32 m0, s40
	s_nop 0
	global_load_lds_dwordx4 v[218:219], off
	s_waitcnt vmcnt(8)
	s_waitcnt lgkmcnt(0)
	s_setprio 1
	s_barrier

	v_mfma_f32_16x16x32_bf16 v[62:65], v[146:149], v[178:181], v[62:65]
	v_mfma_f32_16x16x32_bf16 v[62:65], v[150:153], v[182:185], v[62:65]
	v_mfma_f32_16x16x32_bf16 v[58:61], v[154:157], v[178:181], v[58:61]
	v_mfma_f32_16x16x32_bf16 v[58:61], v[158:161], v[182:185], v[58:61]
	v_mfma_f32_16x16x32_bf16 v[50:53], v[146:149], v[192:195], v[50:53]
	v_mfma_f32_16x16x32_bf16 v[50:53], v[150:153], v[196:199], v[50:53]
	v_mfma_f32_16x16x32_bf16 v[42:45], v[154:157], v[192:195], v[42:45]
	v_mfma_f32_16x16x32_bf16 v[42:45], v[158:161], v[196:199], v[42:45]
	v_mfma_f32_16x16x32_bf16 v[34:37], v[146:149], v[200:203], v[34:37]
	v_mfma_f32_16x16x32_bf16 v[34:37], v[150:153], v[204:207], v[34:37]
	v_mfma_f32_16x16x32_bf16 v[26:29], v[154:157], v[200:203], v[26:29]
	v_mfma_f32_16x16x32_bf16 v[26:29], v[158:161], v[204:207], v[26:29]
	v_mfma_f32_16x16x32_bf16 v[18:21], v[146:149], v[208:211], v[18:21]
	v_mfma_f32_16x16x32_bf16 v[18:21], v[150:153], v[212:215], v[18:21]
	v_mfma_f32_16x16x32_bf16 v[10:13], v[154:157], v[208:211], v[10:13]
	v_mfma_f32_16x16x32_bf16 v[10:13], v[158:161], v[212:215], v[10:13]


	v_mfma_f32_16x16x32_bf16 v[54:57], v[162:165], v[178:181], v[54:57]
	v_mfma_f32_16x16x32_bf16 v[54:57], v[166:169], v[182:185], v[54:57]
	v_mfma_f32_16x16x32_bf16 v[46:49], v[170:173], v[178:181], v[46:49]
	v_mfma_f32_16x16x32_bf16 v[46:49], v[174:177], v[182:185], v[46:49]
	v_mfma_f32_16x16x32_bf16 v[38:41], v[162:165], v[192:195], v[38:41]
	v_mfma_f32_16x16x32_bf16 v[38:41], v[166:169], v[196:199], v[38:41]
	v_mfma_f32_16x16x32_bf16 v[30:33], v[170:173], v[192:195], v[30:33]
	v_mfma_f32_16x16x32_bf16 v[30:33], v[174:177], v[196:199], v[30:33]
	v_mfma_f32_16x16x32_bf16 v[22:25], v[162:165], v[200:203], v[22:25]
	v_mfma_f32_16x16x32_bf16 v[22:25], v[166:169], v[204:207], v[22:25]
	v_mfma_f32_16x16x32_bf16 v[14:17], v[170:173], v[200:203], v[14:17]
	v_mfma_f32_16x16x32_bf16 v[14:17], v[174:177], v[204:207], v[14:17]
	v_mfma_f32_16x16x32_bf16 v[6:9], v[162:165], v[208:211], v[6:9]
	v_mfma_f32_16x16x32_bf16 v[6:9], v[166:169], v[212:215], v[6:9]
	v_mfma_f32_16x16x32_bf16 v[2:5], v[170:173], v[208:211], v[2:5]
	v_mfma_f32_16x16x32_bf16 v[2:5], v[174:177], v[212:215], v[2:5]
	s_barrier
	s_setprio 0
	s_add_i32 s0, 0, 0x18000
	s_add_i32 s1, 0, 0x1c000
	v_add_u32_e32 v158, s0, v144
	v_add_u32_e32 v174, s1, v144
	ds_read_b128 v[146:149], v158
	ds_read_b128 v[150:153], v158 offset:1024
	ds_read_b128 v[154:157], v158 offset:2048
	ds_read_b128 v[158:161], v158 offset:3072
	ds_read_b128 v[162:165], v174
	ds_read_b128 v[166:169], v174 offset:1024
	ds_read_b128 v[170:173], v174 offset:2048
	ds_read_b128 v[174:177], v174 offset:3072
	s_add_u32 s30, s30, 0x80000
	s_addc_u32 s31, s31, 0
	s_mov_b32 m0, s41
	v_lshl_add_u64 v[220:221], s[30:31], 0, v[134:135]
	ds_read_b128 v[178:181], v145 offset:32768
	ds_read_b128 v[182:185], v145 offset:33792
	ds_read_b128 v[192:195], v145 offset:34816
	ds_read_b128 v[196:199], v145 offset:35840
	ds_read_b128 v[200:203], v145 offset:36864
	ds_read_b128 v[204:207], v145 offset:37888
	ds_read_b128 v[208:211], v145 offset:38912
	ds_read_b128 v[212:215], v145 offset:39936
	global_load_lds_dwordx4 v[220:221], off
	v_lshl_add_u64 v[220:221], s[30:31], 0, v[132:133]
	s_mov_b32 m0, s42
	s_nop 0
	global_load_lds_dwordx4 v[220:221], off
	s_waitcnt vmcnt(8)
	s_waitcnt lgkmcnt(0)
	s_setprio 1
	s_barrier

	v_mfma_f32_16x16x32_bf16 v[126:129], v[146:149], v[178:181], v[126:129]
	v_mfma_f32_16x16x32_bf16 v[126:129], v[150:153], v[182:185], v[126:129]
	v_mfma_f32_16x16x32_bf16 v[122:125], v[154:157], v[178:181], v[122:125]
	v_mfma_f32_16x16x32_bf16 v[122:125], v[158:161], v[182:185], v[122:125]
	v_mfma_f32_16x16x32_bf16 v[114:117], v[146:149], v[192:195], v[114:117]
	v_mfma_f32_16x16x32_bf16 v[114:117], v[150:153], v[196:199], v[114:117]
	v_mfma_f32_16x16x32_bf16 v[106:109], v[154:157], v[192:195], v[106:109]
	v_mfma_f32_16x16x32_bf16 v[106:109], v[158:161], v[196:199], v[106:109]
	v_mfma_f32_16x16x32_bf16 v[98:101], v[146:149], v[200:203], v[98:101]
	v_mfma_f32_16x16x32_bf16 v[98:101], v[150:153], v[204:207], v[98:101]
	v_mfma_f32_16x16x32_bf16 v[90:93], v[154:157], v[200:203], v[90:93]
	v_mfma_f32_16x16x32_bf16 v[90:93], v[158:161], v[204:207], v[90:93]
	v_mfma_f32_16x16x32_bf16 v[82:85], v[146:149], v[208:211], v[82:85]
	v_mfma_f32_16x16x32_bf16 v[82:85], v[150:153], v[212:215], v[82:85]
	v_mfma_f32_16x16x32_bf16 v[74:77], v[154:157], v[208:211], v[74:77]
	v_mfma_f32_16x16x32_bf16 v[74:77], v[158:161], v[212:215], v[74:77]


	v_mfma_f32_16x16x32_bf16 v[118:121], v[162:165], v[178:181], v[118:121]
	v_mfma_f32_16x16x32_bf16 v[118:121], v[166:169], v[182:185], v[118:121]
	v_mfma_f32_16x16x32_bf16 v[110:113], v[170:173], v[178:181], v[110:113]
	v_mfma_f32_16x16x32_bf16 v[110:113], v[174:177], v[182:185], v[110:113]
	v_mfma_f32_16x16x32_bf16 v[102:105], v[162:165], v[192:195], v[102:105]
	v_mfma_f32_16x16x32_bf16 v[102:105], v[166:169], v[196:199], v[102:105]
	v_mfma_f32_16x16x32_bf16 v[94:97], v[170:173], v[192:195], v[94:97]
	v_mfma_f32_16x16x32_bf16 v[94:97], v[174:177], v[196:199], v[94:97]
	v_mfma_f32_16x16x32_bf16 v[86:89], v[162:165], v[200:203], v[86:89]
	v_mfma_f32_16x16x32_bf16 v[86:89], v[166:169], v[204:207], v[86:89]
	v_mfma_f32_16x16x32_bf16 v[78:81], v[170:173], v[200:203], v[78:81]
	v_mfma_f32_16x16x32_bf16 v[78:81], v[174:177], v[204:207], v[78:81]
	v_mfma_f32_16x16x32_bf16 v[70:73], v[162:165], v[208:211], v[70:73]
	v_mfma_f32_16x16x32_bf16 v[70:73], v[166:169], v[212:215], v[70:73]
	v_mfma_f32_16x16x32_bf16 v[66:69], v[170:173], v[208:211], v[66:69]
	v_mfma_f32_16x16x32_bf16 v[66:69], v[174:177], v[212:215], v[66:69]
	s_barrier
	s_setprio 0
	s_add_i32 s0, s0, s39
	v_lshl_add_u64 v[140:141], v[140:141], 0, s[84:85]
	s_mov_b32 m0, s0
	ds_read_b128 v[178:181], v145 offset:49152
	ds_read_b128 v[182:185], v145 offset:50176
	ds_read_b128 v[192:195], v145 offset:51200
	ds_read_b128 v[196:199], v145 offset:52224
	ds_read_b128 v[200:203], v145 offset:53248
	ds_read_b128 v[204:207], v145 offset:54272
	ds_read_b128 v[208:211], v145 offset:55296
	ds_read_b128 v[212:215], v145 offset:56320
	global_load_lds_dwordx4 v[140:141], off
	s_add_i32 m0, s0, 0x2000
	s_add_u32 s28, s28, 0x80080
	v_lshl_add_u64 v[140:141], v[188:189], 0, s[84:85]
	s_addc_u32 s29, s29, 0
	s_add_i32 s0, s1, s39
	global_load_lds_dwordx4 v[140:141], off
	v_lshl_add_u64 v[140:141], s[28:29], 0, v[186:187]
	s_mov_b32 m0, s0
	s_nop 0
	global_load_lds_dwordx4 v[140:141], off
	v_lshl_add_u64 v[140:141], s[28:29], 0, v[130:131]
	s_add_i32 m0, s0, 0x2000
	s_nop 0
	global_load_lds_dwordx4 v[140:141], off
	v_lshl_add_u64 v[140:141], v[216:217], 0, s[84:85]
	s_mov_b32 m0, s43
	s_nop 0
	global_load_lds_dwordx4 v[140:141], off
	v_lshl_add_u64 v[140:141], v[218:219], 0, s[84:85]
	s_mov_b32 m0, s44
	s_nop 0
	global_load_lds_dwordx4 v[140:141], off
	s_waitcnt vmcnt(8)
	s_waitcnt lgkmcnt(0)
	s_setprio 1
	s_barrier

	v_mfma_f32_16x16x32_bf16 v[62:65], v[146:149], v[178:181], v[62:65]
	v_mfma_f32_16x16x32_bf16 v[62:65], v[150:153], v[182:185], v[62:65]
	v_mfma_f32_16x16x32_bf16 v[58:61], v[154:157], v[178:181], v[58:61]
	v_mfma_f32_16x16x32_bf16 v[58:61], v[158:161], v[182:185], v[58:61]
	v_mfma_f32_16x16x32_bf16 v[50:53], v[146:149], v[192:195], v[50:53]
	v_mfma_f32_16x16x32_bf16 v[50:53], v[150:153], v[196:199], v[50:53]
	v_mfma_f32_16x16x32_bf16 v[42:45], v[154:157], v[192:195], v[42:45]
	v_mfma_f32_16x16x32_bf16 v[42:45], v[158:161], v[196:199], v[42:45]
	v_mfma_f32_16x16x32_bf16 v[34:37], v[146:149], v[200:203], v[34:37]
	v_mfma_f32_16x16x32_bf16 v[34:37], v[150:153], v[204:207], v[34:37]
	v_mfma_f32_16x16x32_bf16 v[26:29], v[154:157], v[200:203], v[26:29]
	v_mfma_f32_16x16x32_bf16 v[26:29], v[158:161], v[204:207], v[26:29]
	v_mfma_f32_16x16x32_bf16 v[18:21], v[146:149], v[208:211], v[18:21]
	v_mfma_f32_16x16x32_bf16 v[18:21], v[150:153], v[212:215], v[18:21]
	v_mfma_f32_16x16x32_bf16 v[10:13], v[154:157], v[208:211], v[10:13]
	v_mfma_f32_16x16x32_bf16 v[10:13], v[158:161], v[212:215], v[10:13]


	v_mfma_f32_16x16x32_bf16 v[54:57], v[162:165], v[178:181], v[54:57]
	v_mfma_f32_16x16x32_bf16 v[54:57], v[166:169], v[182:185], v[54:57]
	v_mfma_f32_16x16x32_bf16 v[46:49], v[170:173], v[178:181], v[46:49]
	v_mfma_f32_16x16x32_bf16 v[46:49], v[174:177], v[182:185], v[46:49]
	v_mfma_f32_16x16x32_bf16 v[38:41], v[162:165], v[192:195], v[38:41]
	v_mfma_f32_16x16x32_bf16 v[38:41], v[166:169], v[196:199], v[38:41]
	v_mfma_f32_16x16x32_bf16 v[30:33], v[170:173], v[192:195], v[30:33]
	v_mfma_f32_16x16x32_bf16 v[30:33], v[174:177], v[196:199], v[30:33]
	v_mfma_f32_16x16x32_bf16 v[22:25], v[162:165], v[200:203], v[22:25]
	v_mfma_f32_16x16x32_bf16 v[22:25], v[166:169], v[204:207], v[22:25]
	v_mfma_f32_16x16x32_bf16 v[14:17], v[170:173], v[200:203], v[14:17]
	v_mfma_f32_16x16x32_bf16 v[14:17], v[174:177], v[204:207], v[14:17]
	v_mfma_f32_16x16x32_bf16 v[6:9], v[162:165], v[208:211], v[6:9]
	v_mfma_f32_16x16x32_bf16 v[6:9], v[166:169], v[212:215], v[6:9]
	v_mfma_f32_16x16x32_bf16 v[2:5], v[170:173], v[208:211], v[2:5]
	v_mfma_f32_16x16x32_bf16 v[2:5], v[174:177], v[212:215], v[2:5]
	s_barrier
	s_setprio 0
	s_add_i32 s55, s55, 2
	s_add_u32 s26, s26, 0x100
	s_addc_u32 s27, s27, 0
	s_add_u32 s53, s53, 0x100
	s_addc_u32 s54, s54, 0
	s_cmp_gt_u32 s55, 29
	s_cbranch_scc0 .LBB0_443
	s_and_b64 vcc, exec, s[14:15]
	s_cbranch_vccz .LBB0_446
	s_barrier

.LBB0_1126:
	s_add_u32 s0, s28, 0xfff80080
	s_addc_u32 s1, s29, -1
	s_add_i32 s54, 0, 0x10000
	s_cmp_eq_u32 s53, 28
	s_cselect_b32 s35, s19, s1
	s_cselect_b32 s34, s25, s0
	s_cselect_b32 s31, s17, s52
	s_cselect_b32 s30, s27, s51
	s_add_i32 s55, 0, 0x14000
	v_add_u32_e32 v126, s54, v237
	v_add_u32_e32 v158, s55, v237
	ds_read_b128 v[90:93], v126
	ds_read_b128 v[102:105], v126 offset:1024
	ds_read_b128 v[114:117], v126 offset:2048
	ds_read_b128 v[126:129], v126 offset:3072
	ds_read_b128 v[138:141], v158
	ds_read_b128 v[142:145], v158 offset:1024
	ds_read_b128 v[154:157], v158 offset:2048
	ds_read_b128 v[158:161], v158 offset:3072
	v_lshl_add_u64 v[188:189], s[28:29], 0, v[198:199]
	s_add_i32 m0, s40, 0xc000
	ds_read_b128 v[162:165], v238
	ds_read_b128 v[166:169], v238 offset:1024
	ds_read_b128 v[170:173], v238 offset:2048
	ds_read_b128 v[174:177], v238 offset:3072
	ds_read_b128 v[178:181], v238 offset:4096
	ds_read_b128 v[182:185], v238 offset:5120
	ds_read_b128 v[202:205], v238 offset:6144
	ds_read_b128 v[206:209], v238 offset:7168
	global_load_lds_dwordx4 v[188:189], off
	v_lshl_add_u64 v[188:189], s[28:29], 0, v[200:201]
	s_add_i32 m0, s40, 0xe000
	s_nop 0
	global_load_lds_dwordx4 v[188:189], off
	s_waitcnt vmcnt(8)
	s_waitcnt lgkmcnt(0)
	s_setprio 1
	s_barrier

	v_mfma_f32_16x16x32_bf16 v[150:153], v[90:93], v[162:165], v[150:153]
	v_mfma_f32_16x16x32_bf16 v[150:153], v[102:105], v[166:169], v[150:153]
	v_mfma_f32_16x16x32_bf16 v[146:149], v[114:117], v[162:165], v[146:149]
	v_mfma_f32_16x16x32_bf16 v[146:149], v[126:129], v[166:169], v[146:149]
	v_mfma_f32_16x16x32_bf16 v[122:125], v[90:93], v[170:173], v[122:125]
	v_mfma_f32_16x16x32_bf16 v[122:125], v[102:105], v[174:177], v[122:125]
	v_mfma_f32_16x16x32_bf16 v[118:121], v[114:117], v[170:173], v[118:121]
	v_mfma_f32_16x16x32_bf16 v[118:121], v[126:129], v[174:177], v[118:121]
	v_mfma_f32_16x16x32_bf16 v[98:101], v[90:93], v[178:181], v[98:101]
	v_mfma_f32_16x16x32_bf16 v[98:101], v[102:105], v[182:185], v[98:101]
	v_mfma_f32_16x16x32_bf16 v[94:97], v[114:117], v[178:181], v[94:97]
	v_mfma_f32_16x16x32_bf16 v[94:97], v[126:129], v[182:185], v[94:97]
	v_mfma_f32_16x16x32_bf16 v[78:81], v[90:93], v[202:205], v[78:81]
	v_mfma_f32_16x16x32_bf16 v[78:81], v[102:105], v[206:209], v[78:81]
	v_mfma_f32_16x16x32_bf16 v[74:77], v[114:117], v[202:205], v[74:77]
	v_mfma_f32_16x16x32_bf16 v[74:77], v[126:129], v[206:209], v[74:77]


	v_mfma_f32_16x16x32_bf16 v[134:137], v[138:141], v[162:165], v[134:137]
	v_mfma_f32_16x16x32_bf16 v[134:137], v[142:145], v[166:169], v[134:137]
	v_mfma_f32_16x16x32_bf16 v[130:133], v[154:157], v[162:165], v[130:133]
	v_mfma_f32_16x16x32_bf16 v[130:133], v[158:161], v[166:169], v[130:133]
	v_mfma_f32_16x16x32_bf16 v[110:113], v[138:141], v[170:173], v[110:113]
	v_mfma_f32_16x16x32_bf16 v[110:113], v[142:145], v[174:177], v[110:113]
	v_mfma_f32_16x16x32_bf16 v[106:109], v[154:157], v[170:173], v[106:109]
	v_mfma_f32_16x16x32_bf16 v[106:109], v[158:161], v[174:177], v[106:109]
	v_mfma_f32_16x16x32_bf16 v[86:89], v[138:141], v[178:181], v[86:89]
	v_mfma_f32_16x16x32_bf16 v[86:89], v[142:145], v[182:185], v[86:89]
	v_mfma_f32_16x16x32_bf16 v[82:85], v[154:157], v[178:181], v[82:85]
	v_mfma_f32_16x16x32_bf16 v[82:85], v[158:161], v[182:185], v[82:85]
	v_mfma_f32_16x16x32_bf16 v[70:73], v[138:141], v[202:205], v[70:73]
	v_mfma_f32_16x16x32_bf16 v[70:73], v[142:145], v[206:209], v[70:73]
	v_mfma_f32_16x16x32_bf16 v[66:69], v[154:157], v[202:205], v[66:69]
	v_mfma_f32_16x16x32_bf16 v[66:69], v[158:161], v[206:209], v[66:69]
	s_barrier
	s_setprio 0
	s_add_i32 s0, s54, s39
	v_lshl_add_u64 v[188:189], s[30:31], 0, v[186:187]
	s_mov_b32 m0, s0
	ds_read_b128 v[162:165], v238 offset:16384
	ds_read_b128 v[166:169], v238 offset:17408
	ds_read_b128 v[170:173], v238 offset:18432
	ds_read_b128 v[174:177], v238 offset:19456
	ds_read_b128 v[178:181], v238 offset:20480
	ds_read_b128 v[182:185], v238 offset:21504
	ds_read_b128 v[202:205], v238 offset:22528
	ds_read_b128 v[206:209], v238 offset:23552
	global_load_lds_dwordx4 v[188:189], off
	s_add_i32 m0, s0, 0x2000
	s_add_u32 s0, s30, 0x80000
	v_lshl_add_u64 v[210:211], s[30:31], 0, v[196:197]
	s_addc_u32 s1, s31, 0
	s_add_i32 s54, s55, s39
	global_load_lds_dwordx4 v[210:211], off
	v_lshl_add_u64 v[212:213], s[0:1], 0, v[186:187]
	s_mov_b32 m0, s54
	v_lshl_add_u64 v[214:215], s[34:35], 0, v[194:195]
	global_load_lds_dwordx4 v[212:213], off
	v_lshl_add_u64 v[212:213], s[0:1], 0, v[196:197]
	s_add_i32 m0, s54, 0x2000
	s_nop 0
	global_load_lds_dwordx4 v[212:213], off
	v_lshl_add_u64 v[212:213], s[34:35], 0, v[192:193]
	s_mov_b32 m0, s40
	s_nop 0
	global_load_lds_dwordx4 v[212:213], off
	s_mov_b32 m0, s41
	s_nop 0
	global_load_lds_dwordx4 v[214:215], off
	s_waitcnt vmcnt(8)
	s_waitcnt lgkmcnt(0)
	s_setprio 1
	s_barrier

	v_mfma_f32_16x16x32_bf16 v[62:65], v[90:93], v[162:165], v[62:65]
	v_mfma_f32_16x16x32_bf16 v[62:65], v[102:105], v[166:169], v[62:65]
	v_mfma_f32_16x16x32_bf16 v[58:61], v[114:117], v[162:165], v[58:61]
	v_mfma_f32_16x16x32_bf16 v[58:61], v[126:129], v[166:169], v[58:61]
	v_mfma_f32_16x16x32_bf16 v[46:49], v[90:93], v[170:173], v[46:49]
	v_mfma_f32_16x16x32_bf16 v[46:49], v[102:105], v[174:177], v[46:49]
	v_mfma_f32_16x16x32_bf16 v[42:45], v[114:117], v[170:173], v[42:45]
	v_mfma_f32_16x16x32_bf16 v[42:45], v[126:129], v[174:177], v[42:45]
	v_mfma_f32_16x16x32_bf16 v[30:33], v[90:93], v[178:181], v[30:33]
	v_mfma_f32_16x16x32_bf16 v[30:33], v[102:105], v[182:185], v[30:33]
	v_mfma_f32_16x16x32_bf16 v[26:29], v[114:117], v[178:181], v[26:29]
	v_mfma_f32_16x16x32_bf16 v[26:29], v[126:129], v[182:185], v[26:29]
	v_mfma_f32_16x16x32_bf16 v[14:17], v[90:93], v[202:205], v[14:17]
	v_mfma_f32_16x16x32_bf16 v[14:17], v[102:105], v[206:209], v[14:17]
	v_mfma_f32_16x16x32_bf16 v[10:13], v[114:117], v[202:205], v[10:13]
	v_mfma_f32_16x16x32_bf16 v[10:13], v[126:129], v[206:209], v[10:13]


	v_mfma_f32_16x16x32_bf16 v[54:57], v[138:141], v[162:165], v[54:57]
	v_mfma_f32_16x16x32_bf16 v[54:57], v[142:145], v[166:169], v[54:57]
	v_mfma_f32_16x16x32_bf16 v[50:53], v[154:157], v[162:165], v[50:53]
	v_mfma_f32_16x16x32_bf16 v[50:53], v[158:161], v[166:169], v[50:53]
	v_mfma_f32_16x16x32_bf16 v[38:41], v[138:141], v[170:173], v[38:41]
	v_mfma_f32_16x16x32_bf16 v[38:41], v[142:145], v[174:177], v[38:41]
	v_mfma_f32_16x16x32_bf16 v[34:37], v[154:157], v[170:173], v[34:37]
	v_mfma_f32_16x16x32_bf16 v[34:37], v[158:161], v[174:177], v[34:37]
	v_mfma_f32_16x16x32_bf16 v[22:25], v[138:141], v[178:181], v[22:25]
	v_mfma_f32_16x16x32_bf16 v[22:25], v[142:145], v[182:185], v[22:25]
	v_mfma_f32_16x16x32_bf16 v[18:21], v[154:157], v[178:181], v[18:21]
	v_mfma_f32_16x16x32_bf16 v[18:21], v[158:161], v[182:185], v[18:21]
	v_mfma_f32_16x16x32_bf16 v[6:9], v[138:141], v[202:205], v[6:9]
	v_mfma_f32_16x16x32_bf16 v[6:9], v[142:145], v[206:209], v[6:9]
	v_mfma_f32_16x16x32_bf16 v[2:5], v[154:157], v[202:205], v[2:5]
	v_mfma_f32_16x16x32_bf16 v[2:5], v[158:161], v[206:209], v[2:5]
	s_barrier
	s_setprio 0
	s_add_i32 s54, 0, 0x18000
	s_add_i32 s55, 0, 0x1c000
	v_add_u32_e32 v126, s54, v237
	v_add_u32_e32 v158, s55, v237
	ds_read_b128 v[90:93], v126
	ds_read_b128 v[102:105], v126 offset:1024
	ds_read_b128 v[114:117], v126 offset:2048
	ds_read_b128 v[126:129], v126 offset:3072
	ds_read_b128 v[138:141], v158
	ds_read_b128 v[142:145], v158 offset:1024
	ds_read_b128 v[154:157], v158 offset:2048
	ds_read_b128 v[158:161], v158 offset:3072
	s_add_u32 s0, s34, 0x80000
	s_addc_u32 s1, s35, 0
	s_mov_b32 m0, s42
	v_lshl_add_u64 v[216:217], s[0:1], 0, v[192:193]
	ds_read_b128 v[162:165], v238 offset:32768
	ds_read_b128 v[166:169], v238 offset:33792
	ds_read_b128 v[170:173], v238 offset:34816
	ds_read_b128 v[174:177], v238 offset:35840
	ds_read_b128 v[178:181], v238 offset:36864
	ds_read_b128 v[182:185], v238 offset:37888
	ds_read_b128 v[202:205], v238 offset:38912
	ds_read_b128 v[206:209], v238 offset:39936
	global_load_lds_dwordx4 v[216:217], off
	v_lshl_add_u64 v[216:217], s[0:1], 0, v[194:195]
	s_mov_b32 m0, s43
	s_nop 0
	global_load_lds_dwordx4 v[216:217], off
	s_waitcnt vmcnt(8)
	s_waitcnt lgkmcnt(0)
	s_setprio 1
	s_barrier

	v_mfma_f32_16x16x32_bf16 v[150:153], v[90:93], v[162:165], v[150:153]
	v_mfma_f32_16x16x32_bf16 v[150:153], v[102:105], v[166:169], v[150:153]
	v_mfma_f32_16x16x32_bf16 v[146:149], v[114:117], v[162:165], v[146:149]
	v_mfma_f32_16x16x32_bf16 v[146:149], v[126:129], v[166:169], v[146:149]
	v_mfma_f32_16x16x32_bf16 v[122:125], v[90:93], v[170:173], v[122:125]
	v_mfma_f32_16x16x32_bf16 v[122:125], v[102:105], v[174:177], v[122:125]
	v_mfma_f32_16x16x32_bf16 v[118:121], v[114:117], v[170:173], v[118:121]
	v_mfma_f32_16x16x32_bf16 v[118:121], v[126:129], v[174:177], v[118:121]
	v_mfma_f32_16x16x32_bf16 v[98:101], v[90:93], v[178:181], v[98:101]
	v_mfma_f32_16x16x32_bf16 v[98:101], v[102:105], v[182:185], v[98:101]
	v_mfma_f32_16x16x32_bf16 v[94:97], v[114:117], v[178:181], v[94:97]
	v_mfma_f32_16x16x32_bf16 v[94:97], v[126:129], v[182:185], v[94:97]
	v_mfma_f32_16x16x32_bf16 v[78:81], v[90:93], v[202:205], v[78:81]
	v_mfma_f32_16x16x32_bf16 v[78:81], v[102:105], v[206:209], v[78:81]
	v_mfma_f32_16x16x32_bf16 v[74:77], v[114:117], v[202:205], v[74:77]
	v_mfma_f32_16x16x32_bf16 v[74:77], v[126:129], v[206:209], v[74:77]


	v_mfma_f32_16x16x32_bf16 v[134:137], v[138:141], v[162:165], v[134:137]
	v_mfma_f32_16x16x32_bf16 v[134:137], v[142:145], v[166:169], v[134:137]
	v_mfma_f32_16x16x32_bf16 v[130:133], v[154:157], v[162:165], v[130:133]
	v_mfma_f32_16x16x32_bf16 v[130:133], v[158:161], v[166:169], v[130:133]
	v_mfma_f32_16x16x32_bf16 v[110:113], v[138:141], v[170:173], v[110:113]
	v_mfma_f32_16x16x32_bf16 v[110:113], v[142:145], v[174:177], v[110:113]
	v_mfma_f32_16x16x32_bf16 v[106:109], v[154:157], v[170:173], v[106:109]
	v_mfma_f32_16x16x32_bf16 v[106:109], v[158:161], v[174:177], v[106:109]
	v_mfma_f32_16x16x32_bf16 v[86:89], v[138:141], v[178:181], v[86:89]
	v_mfma_f32_16x16x32_bf16 v[86:89], v[142:145], v[182:185], v[86:89]
	v_mfma_f32_16x16x32_bf16 v[82:85], v[154:157], v[178:181], v[82:85]
	v_mfma_f32_16x16x32_bf16 v[82:85], v[158:161], v[182:185], v[82:85]
	v_mfma_f32_16x16x32_bf16 v[70:73], v[138:141], v[202:205], v[70:73]
	v_mfma_f32_16x16x32_bf16 v[70:73], v[142:145], v[206:209], v[70:73]
	v_mfma_f32_16x16x32_bf16 v[66:69], v[154:157], v[202:205], v[66:69]
	v_mfma_f32_16x16x32_bf16 v[66:69], v[158:161], v[206:209], v[66:69]
	s_barrier
	s_setprio 0
	s_add_i32 s0, s54, s39
	v_lshl_add_u64 v[188:189], v[188:189], 0, s[84:85]
	s_mov_b32 m0, s0
	ds_read_b128 v[162:165], v238 offset:49152
	ds_read_b128 v[166:169], v238 offset:50176
	ds_read_b128 v[170:173], v238 offset:51200
	ds_read_b128 v[174:177], v238 offset:52224
	ds_read_b128 v[178:181], v238 offset:53248
	ds_read_b128 v[182:185], v238 offset:54272
	ds_read_b128 v[202:205], v238 offset:55296
	ds_read_b128 v[206:209], v238 offset:56320
	global_load_lds_dwordx4 v[188:189], off
	s_add_i32 m0, s0, 0x2000
	s_add_u32 s0, s30, 0x80080
	v_lshl_add_u64 v[188:189], v[210:211], 0, s[84:85]
	s_addc_u32 s1, s31, 0
	s_add_i32 s30, s55, s39
	global_load_lds_dwordx4 v[188:189], off
	v_lshl_add_u64 v[188:189], s[0:1], 0, v[186:187]
	s_mov_b32 m0, s30
	s_nop 0
	global_load_lds_dwordx4 v[188:189], off
	v_lshl_add_u64 v[188:189], s[0:1], 0, v[196:197]
	s_add_i32 m0, s30, 0x2000
	s_nop 0
	global_load_lds_dwordx4 v[188:189], off
	v_lshl_add_u64 v[188:189], v[212:213], 0, s[84:85]
	s_mov_b32 m0, s47
	s_nop 0
	global_load_lds_dwordx4 v[188:189], off
	v_lshl_add_u64 v[188:189], v[214:215], 0, s[84:85]
	s_mov_b32 m0, s48
	s_nop 0
	global_load_lds_dwordx4 v[188:189], off
	s_waitcnt vmcnt(8)
	s_waitcnt lgkmcnt(0)
	s_setprio 1
	s_barrier

	v_mfma_f32_16x16x32_bf16 v[62:65], v[90:93], v[162:165], v[62:65]
	v_mfma_f32_16x16x32_bf16 v[62:65], v[102:105], v[166:169], v[62:65]
	v_mfma_f32_16x16x32_bf16 v[58:61], v[114:117], v[162:165], v[58:61]
	v_mfma_f32_16x16x32_bf16 v[58:61], v[126:129], v[166:169], v[58:61]
	v_mfma_f32_16x16x32_bf16 v[46:49], v[90:93], v[170:173], v[46:49]
	v_mfma_f32_16x16x32_bf16 v[46:49], v[102:105], v[174:177], v[46:49]
	v_mfma_f32_16x16x32_bf16 v[42:45], v[114:117], v[170:173], v[42:45]
	v_mfma_f32_16x16x32_bf16 v[42:45], v[126:129], v[174:177], v[42:45]
	v_mfma_f32_16x16x32_bf16 v[30:33], v[90:93], v[178:181], v[30:33]
	v_mfma_f32_16x16x32_bf16 v[30:33], v[102:105], v[182:185], v[30:33]
	v_mfma_f32_16x16x32_bf16 v[26:29], v[114:117], v[178:181], v[26:29]
	v_mfma_f32_16x16x32_bf16 v[26:29], v[126:129], v[182:185], v[26:29]
	v_mfma_f32_16x16x32_bf16 v[14:17], v[90:93], v[202:205], v[14:17]
	v_mfma_f32_16x16x32_bf16 v[14:17], v[102:105], v[206:209], v[14:17]
	v_mfma_f32_16x16x32_bf16 v[10:13], v[114:117], v[202:205], v[10:13]
	v_mfma_f32_16x16x32_bf16 v[10:13], v[126:129], v[206:209], v[10:13]


	v_mfma_f32_16x16x32_bf16 v[54:57], v[138:141], v[162:165], v[54:57]
	v_mfma_f32_16x16x32_bf16 v[54:57], v[142:145], v[166:169], v[54:57]
	v_mfma_f32_16x16x32_bf16 v[50:53], v[154:157], v[162:165], v[50:53]
	v_mfma_f32_16x16x32_bf16 v[50:53], v[158:161], v[166:169], v[50:53]
	v_mfma_f32_16x16x32_bf16 v[38:41], v[138:141], v[170:173], v[38:41]
	v_mfma_f32_16x16x32_bf16 v[38:41], v[142:145], v[174:177], v[38:41]
	v_mfma_f32_16x16x32_bf16 v[34:37], v[154:157], v[170:173], v[34:37]
	v_mfma_f32_16x16x32_bf16 v[34:37], v[158:161], v[174:177], v[34:37]
	v_mfma_f32_16x16x32_bf16 v[22:25], v[138:141], v[178:181], v[22:25]
	v_mfma_f32_16x16x32_bf16 v[22:25], v[142:145], v[182:185], v[22:25]
	v_mfma_f32_16x16x32_bf16 v[18:21], v[154:157], v[178:181], v[18:21]
	v_mfma_f32_16x16x32_bf16 v[18:21], v[158:161], v[182:185], v[18:21]
	v_mfma_f32_16x16x32_bf16 v[6:9], v[138:141], v[202:205], v[6:9]
	v_mfma_f32_16x16x32_bf16 v[6:9], v[142:145], v[206:209], v[6:9]
	v_mfma_f32_16x16x32_bf16 v[2:5], v[154:157], v[202:205], v[2:5]
	v_mfma_f32_16x16x32_bf16 v[2:5], v[158:161], v[206:209], v[2:5]
	s_barrier
	s_setprio 0
	s_add_i32 s53, s53, 2
	s_add_u32 s28, s28, 0x100
	s_addc_u32 s29, s29, 0
	s_add_u32 s51, s51, 0x100
	s_addc_u32 s52, s52, 0
	s_cmp_gt_u32 s53, 29
	s_cbranch_scc0 .LBB0_1126
	s_and_b64 vcc, exec, s[14:15]
	s_cbranch_vccz .LBB0_1129
	s_barrier
